# attention epilogue rows: counted waits (8 K loads + stores so far) instead of vmcnt(0..7): the next item's K loads stay in flight across the rows for g>0; no-next path drains explicitly
# speedup vs baseline: 1.0115x; 1.0115x over previous
.LBB0_1210:
	v_add_co_u32_e32 v16, vcc, 0x8000, v40
	s_mov_b32 s4, 0x10000
	s_nop 0
	v_addc_co_u32_e32 v17, vcc, 0, v41, vcc
	v_add_co_u32_e32 v20, vcc, 0xa000, v40
	s_nop 1
	v_addc_co_u32_e32 v21, vcc, 0, v41, vcc
	v_add_co_u32_e32 v24, vcc, 0xc000, v40
	global_load_dwordx4 v[16:19], v[16:17], off
	s_nop 0
	global_load_dwordx4 v[20:23], v[20:21], off
	v_addc_co_u32_e32 v25, vcc, 0, v41, vcc
	v_add_co_u32_e32 v28, vcc, 0xe000, v40
	s_nop 1
	v_addc_co_u32_e32 v29, vcc, 0, v41, vcc
	v_add_co_u32_e32 v32, vcc, s4, v40
	s_mov_b32 s4, 0x12000
	s_nop 0
	v_addc_co_u32_e32 v33, vcc, 0, v41, vcc
	v_add_co_u32_e32 v36, vcc, s4, v40
	s_mov_b32 s4, 0x14000
	s_nop 0
	v_addc_co_u32_e32 v37, vcc, 0, v41, vcc
	v_add_co_u32_e32 v42, vcc, s4, v40
	global_load_dwordx4 v[24:27], v[24:25], off
	s_nop 0
	global_load_dwordx4 v[28:31], v[28:29], off
	v_addc_co_u32_e32 v43, vcc, 0, v41, vcc
	v_add_co_u32_e32 v44, vcc, s51, v40
	global_load_dwordx4 v[32:35], v[32:33], off
	s_nop 0
	global_load_dwordx4 v[36:39], v[36:37], off
	v_addc_co_u32_e32 v45, vcc, 0, v41, vcc
	global_load_dwordx4 v[40:43], v[42:43], off
	s_nop 0
	global_load_dwordx4 v[44:47], v[44:45], off
	s_branch .LBB0_1211

.LBB0_1211:
	v_readlane_b32 s4, v253, 51
	s_and_b64 vcc, exec, s[24:25]
	s_nop 0
	v_lshl_add_u32 v48, v193, 5, s4
	s_movk_i32 s4, 0x210
	v_mul_lo_u32 v49, v192, s4
	v_add_u32_e32 v57, v48, v49
	ds_read_b128 v[52:55], v57
	ds_read_b128 v[48:51], v57 offset:16
	v_readlane_b32 s4, v253, 47
	s_nop 1
	v_lshl_add_u32 v56, v192, 2, s4
	s_cbranch_vccz .LBB0_1213
	ds_read_b32 v58, v56
	s_waitcnt vmcnt(8)
	v_lshlrev_b32_e32 v60, 16, v84
	v_and_b32_e32 v61, 0xffff0000, v84
	s_waitcnt lgkmcnt(0)
	v_pk_fma_f32 v[52:53], v[58:59], v[60:61], v[52:53] op_sel_hi:[0,1,1]
	v_lshlrev_b32_e32 v60, 16, v85
	v_and_b32_e32 v61, 0xffff0000, v85
	v_pk_fma_f32 v[54:55], v[58:59], v[60:61], v[54:55] op_sel_hi:[0,1,1]
	v_lshlrev_b32_e32 v60, 16, v86
	v_and_b32_e32 v61, 0xffff0000, v86
	v_pk_fma_f32 v[48:49], v[58:59], v[60:61], v[48:49] op_sel_hi:[0,1,1]
	v_lshlrev_b32_e32 v60, 16, v87
	v_and_b32_e32 v61, 0xffff0000, v87
	v_pk_fma_f32 v[50:51], v[58:59], v[60:61], v[50:51] op_sel_hi:[0,1,1]
.LBB0_1213:
	s_and_b64 vcc, exec, s[46:47]
	s_cbranch_vccnz .LBB0_1215
	s_waitcnt vmcnt(8)
	v_lshlrev_b32_e32 v86, 16, v126
	v_and_b32_e32 v87, 0xffff0000, v126
	v_lshlrev_b32_e32 v126, 16, v127
	v_lshlrev_b32_e32 v58, 16, v124
	v_and_b32_e32 v59, 0xffff0000, v124
	v_lshlrev_b32_e32 v62, 16, v125
	v_and_b32_e32 v63, 0xffff0000, v125
	v_and_b32_e32 v127, 0xffff0000, v127
	v_mul_f32_e32 v138, 0xbfb8aa3b, v126
	v_mul_f32_e32 v60, 0xbfb8aa3b, v58
	v_mul_f32_e32 v61, 0xbfb8aa3b, v59
	v_mul_f32_e32 v84, 0xbfb8aa3b, v62
	v_mul_f32_e32 v85, 0xbfb8aa3b, v63
	v_mul_f32_e32 v124, 0xbfb8aa3b, v86
	v_mul_f32_e32 v125, 0xbfb8aa3b, v87
	v_exp_f32_e32 v138, v138
	v_mul_f32_e32 v140, 0xbfb8aa3b, v127
	v_exp_f32_e32 v60, v60
	v_exp_f32_e32 v61, v61
	v_exp_f32_e32 v84, v84
	v_exp_f32_e32 v85, v85
	v_exp_f32_e32 v124, v124
	v_exp_f32_e32 v125, v125
	v_exp_f32_e32 v140, v140
	v_add_f32_e32 v138, 1.0, v138
	v_add_f32_e32 v60, 1.0, v60
	v_add_f32_e32 v61, 1.0, v61
	v_add_f32_e32 v84, 1.0, v84
	v_add_f32_e32 v85, 1.0, v85
	v_add_f32_e32 v124, 1.0, v124
	v_add_f32_e32 v125, 1.0, v125
	v_rcp_f32_e32 v144, v138
	v_add_f32_e32 v138, 1.0, v140
	v_rcp_f32_e32 v60, v60
	v_rcp_f32_e32 v61, v61
	v_rcp_f32_e32 v84, v84
	v_rcp_f32_e32 v85, v85
	v_rcp_f32_e32 v124, v124
	v_rcp_f32_e32 v125, v125
	v_rcp_f32_e32 v145, v138
	v_pk_mul_f32 v[58:59], v[60:61], v[58:59]
	v_pk_mul_f32 v[60:61], v[84:85], v[62:63]
	v_pk_mul_f32 v[62:63], v[124:125], v[86:87]
	v_pk_mul_f32 v[84:85], v[144:145], v[126:127]
	s_waitcnt lgkmcnt(1)
	v_pk_mul_f32 v[54:55], v[54:55], v[60:61]
	s_waitcnt lgkmcnt(0)
	v_pk_mul_f32 v[50:51], v[50:51], v[84:85]
	v_pk_mul_f32 v[48:49], v[48:49], v[62:63]
	v_pk_mul_f32 v[52:53], v[52:53], v[58:59]
.LBB0_1215:
	s_waitcnt lgkmcnt(1)
	v_cvt_pk_bf16_f32 v52, v52, v53
	v_cvt_pk_bf16_f32 v53, v54, v55
	s_waitcnt lgkmcnt(0)
	v_cvt_pk_bf16_f32 v54, v48, v49
	v_cvt_pk_bf16_f32 v55, v50, v51
	global_store_dwordx4 v[142:143], v[52:55], off sc1
	ds_read_b128 v[52:55], v57 offset:2112
	ds_read_b128 v[48:51], v57 offset:2128
	s_and_b64 vcc, exec, s[44:45]
	s_cbranch_vccnz .LBB0_1217
	ds_read_b32 v58, v56 offset:16
	s_waitcnt vmcnt(9)
	v_lshlrev_b32_e32 v60, 16, v96
	v_and_b32_e32 v61, 0xffff0000, v96
	s_waitcnt lgkmcnt(0)
	v_pk_fma_f32 v[52:53], v[58:59], v[60:61], v[52:53] op_sel_hi:[0,1,1]
	v_lshlrev_b32_e32 v60, 16, v97
	v_and_b32_e32 v61, 0xffff0000, v97
	v_pk_fma_f32 v[54:55], v[58:59], v[60:61], v[54:55] op_sel_hi:[0,1,1]
	v_lshlrev_b32_e32 v60, 16, v98
	v_and_b32_e32 v61, 0xffff0000, v98
	v_pk_fma_f32 v[48:49], v[58:59], v[60:61], v[48:49] op_sel_hi:[0,1,1]
	v_lshlrev_b32_e32 v60, 16, v99
	v_and_b32_e32 v61, 0xffff0000, v99
	v_pk_fma_f32 v[50:51], v[58:59], v[60:61], v[50:51] op_sel_hi:[0,1,1]
.LBB0_1217:
	s_and_b64 vcc, exec, s[46:47]
	s_cbranch_vccnz .LBB0_1219
	s_waitcnt vmcnt(9)
	v_lshlrev_b32_e32 v58, 16, v120
	v_and_b32_e32 v59, 0xffff0000, v120
	v_lshlrev_b32_e32 v62, 16, v121
	v_and_b32_e32 v63, 0xffff0000, v121
	v_lshlrev_b32_e32 v86, 16, v122
	v_and_b32_e32 v87, 0xffff0000, v122
	v_lshlrev_b32_e32 v98, 16, v123
	v_and_b32_e32 v99, 0xffff0000, v123
	v_mul_f32_e32 v60, 0xbfb8aa3b, v58
	v_mul_f32_e32 v61, 0xbfb8aa3b, v59
	v_mul_f32_e32 v84, 0xbfb8aa3b, v62
	v_mul_f32_e32 v85, 0xbfb8aa3b, v63
	v_mul_f32_e32 v96, 0xbfb8aa3b, v86
	v_mul_f32_e32 v97, 0xbfb8aa3b, v87
	v_mul_f32_e32 v120, 0xbfb8aa3b, v98
	v_mul_f32_e32 v121, 0xbfb8aa3b, v99
	v_exp_f32_e32 v60, v60
	v_exp_f32_e32 v61, v61
	v_exp_f32_e32 v84, v84
	v_exp_f32_e32 v85, v85
	v_exp_f32_e32 v96, v96
	v_exp_f32_e32 v97, v97
	v_exp_f32_e32 v120, v120
	v_exp_f32_e32 v121, v121
	v_add_f32_e32 v60, 1.0, v60
	v_add_f32_e32 v61, 1.0, v61
	v_add_f32_e32 v84, 1.0, v84
	v_add_f32_e32 v85, 1.0, v85
	v_add_f32_e32 v96, 1.0, v96
	v_add_f32_e32 v97, 1.0, v97
	v_add_f32_e32 v120, 1.0, v120
	v_add_f32_e32 v121, 1.0, v121
	v_rcp_f32_e32 v60, v60
	v_rcp_f32_e32 v61, v61
	v_rcp_f32_e32 v84, v84
	v_rcp_f32_e32 v85, v85
	v_rcp_f32_e32 v96, v96
	v_rcp_f32_e32 v97, v97
	v_rcp_f32_e32 v120, v120
	v_rcp_f32_e32 v121, v121
	v_pk_mul_f32 v[58:59], v[60:61], v[58:59]
	v_pk_mul_f32 v[60:61], v[84:85], v[62:63]
	v_pk_mul_f32 v[62:63], v[96:97], v[86:87]
	v_pk_mul_f32 v[84:85], v[120:121], v[98:99]
	s_waitcnt lgkmcnt(1)
	v_pk_mul_f32 v[54:55], v[54:55], v[60:61]
	s_waitcnt lgkmcnt(0)
	v_pk_mul_f32 v[50:51], v[50:51], v[84:85]
	v_pk_mul_f32 v[48:49], v[48:49], v[62:63]
	v_pk_mul_f32 v[52:53], v[52:53], v[58:59]
.LBB0_1219:
	s_waitcnt lgkmcnt(1)
	v_cvt_pk_bf16_f32 v52, v52, v53
	v_cvt_pk_bf16_f32 v53, v54, v55
	s_waitcnt lgkmcnt(0)
	v_cvt_pk_bf16_f32 v54, v48, v49
	v_cvt_pk_bf16_f32 v55, v50, v51
	v_lshl_add_u64 v[48:49], s[0:1], 1, v[142:143]
	global_store_dwordx4 v[48:49], v[52:55], off sc1
	ds_read_b128 v[52:55], v57 offset:4224
	ds_read_b128 v[48:51], v57 offset:4240
	s_and_b64 vcc, exec, s[44:45]
	s_cbranch_vccnz .LBB0_1221
	ds_read_b32 v58, v56 offset:32
	s_waitcnt vmcnt(10)
	v_lshlrev_b32_e32 v60, 16, v88
	v_and_b32_e32 v61, 0xffff0000, v88
	s_waitcnt lgkmcnt(0)
	v_pk_fma_f32 v[52:53], v[58:59], v[60:61], v[52:53] op_sel_hi:[0,1,1]
	v_lshlrev_b32_e32 v60, 16, v89
	v_and_b32_e32 v61, 0xffff0000, v89
	v_pk_fma_f32 v[54:55], v[58:59], v[60:61], v[54:55] op_sel_hi:[0,1,1]
	v_lshlrev_b32_e32 v60, 16, v90
	v_and_b32_e32 v61, 0xffff0000, v90
	v_pk_fma_f32 v[48:49], v[58:59], v[60:61], v[48:49] op_sel_hi:[0,1,1]
	v_lshlrev_b32_e32 v60, 16, v91
	v_and_b32_e32 v61, 0xffff0000, v91
	v_pk_fma_f32 v[50:51], v[58:59], v[60:61], v[50:51] op_sel_hi:[0,1,1]
.LBB0_1221:
	s_and_b64 vcc, exec, s[46:47]
	s_cbranch_vccnz .LBB0_1223
	s_waitcnt vmcnt(10)
	v_lshlrev_b32_e32 v58, 16, v116
	v_and_b32_e32 v59, 0xffff0000, v116
	v_lshlrev_b32_e32 v62, 16, v117
	v_and_b32_e32 v63, 0xffff0000, v117
	v_lshlrev_b32_e32 v86, 16, v118
	v_and_b32_e32 v87, 0xffff0000, v118
	v_lshlrev_b32_e32 v90, 16, v119
	v_and_b32_e32 v91, 0xffff0000, v119
	v_mul_f32_e32 v60, 0xbfb8aa3b, v58
	v_mul_f32_e32 v61, 0xbfb8aa3b, v59
	v_mul_f32_e32 v84, 0xbfb8aa3b, v62
	v_mul_f32_e32 v85, 0xbfb8aa3b, v63
	v_mul_f32_e32 v88, 0xbfb8aa3b, v86
	v_mul_f32_e32 v89, 0xbfb8aa3b, v87
	v_mul_f32_e32 v96, 0xbfb8aa3b, v90
	v_mul_f32_e32 v97, 0xbfb8aa3b, v91
	v_exp_f32_e32 v60, v60
	v_exp_f32_e32 v61, v61
	v_exp_f32_e32 v84, v84
	v_exp_f32_e32 v85, v85
	v_exp_f32_e32 v88, v88
	v_exp_f32_e32 v89, v89
	v_exp_f32_e32 v96, v96
	v_exp_f32_e32 v97, v97
	v_add_f32_e32 v60, 1.0, v60
	v_add_f32_e32 v61, 1.0, v61
	v_add_f32_e32 v84, 1.0, v84
	v_add_f32_e32 v85, 1.0, v85
	v_add_f32_e32 v88, 1.0, v88
	v_add_f32_e32 v89, 1.0, v89
	v_add_f32_e32 v96, 1.0, v96
	v_add_f32_e32 v97, 1.0, v97
	v_rcp_f32_e32 v60, v60
	v_rcp_f32_e32 v61, v61
	v_rcp_f32_e32 v84, v84
	v_rcp_f32_e32 v85, v85
	v_rcp_f32_e32 v88, v88
	v_rcp_f32_e32 v89, v89
	v_rcp_f32_e32 v96, v96
	v_rcp_f32_e32 v97, v97
	v_pk_mul_f32 v[58:59], v[60:61], v[58:59]
	v_pk_mul_f32 v[60:61], v[84:85], v[62:63]
	v_pk_mul_f32 v[62:63], v[88:89], v[86:87]
	v_pk_mul_f32 v[84:85], v[96:97], v[90:91]
	s_waitcnt lgkmcnt(1)
	v_pk_mul_f32 v[54:55], v[54:55], v[60:61]
	s_waitcnt lgkmcnt(0)
	v_pk_mul_f32 v[50:51], v[50:51], v[84:85]
	v_pk_mul_f32 v[48:49], v[48:49], v[62:63]
	v_pk_mul_f32 v[52:53], v[52:53], v[58:59]
.LBB0_1223:
	s_waitcnt lgkmcnt(1)
	v_cvt_pk_bf16_f32 v52, v52, v53
	v_cvt_pk_bf16_f32 v53, v54, v55
	s_waitcnt lgkmcnt(0)
	v_cvt_pk_bf16_f32 v54, v48, v49
	v_cvt_pk_bf16_f32 v55, v50, v51
	v_lshl_add_u64 v[48:49], s[82:83], 1, v[142:143]
	global_store_dwordx4 v[48:49], v[52:55], off sc1
	ds_read_b128 v[52:55], v57 offset:6336
	ds_read_b128 v[48:51], v57 offset:6352
	s_and_b64 vcc, exec, s[44:45]
	s_cbranch_vccnz .LBB0_1225
	ds_read_b32 v58, v56 offset:48
	s_waitcnt vmcnt(11)
	v_lshlrev_b32_e32 v60, 16, v80
	v_and_b32_e32 v61, 0xffff0000, v80
	s_waitcnt lgkmcnt(0)
	v_pk_fma_f32 v[52:53], v[58:59], v[60:61], v[52:53] op_sel_hi:[0,1,1]
	v_lshlrev_b32_e32 v60, 16, v81
	v_and_b32_e32 v61, 0xffff0000, v81
	v_pk_fma_f32 v[54:55], v[58:59], v[60:61], v[54:55] op_sel_hi:[0,1,1]
	v_lshlrev_b32_e32 v60, 16, v82
	v_and_b32_e32 v61, 0xffff0000, v82
	v_pk_fma_f32 v[48:49], v[58:59], v[60:61], v[48:49] op_sel_hi:[0,1,1]
	v_lshlrev_b32_e32 v60, 16, v83
	v_and_b32_e32 v61, 0xffff0000, v83
	v_pk_fma_f32 v[50:51], v[58:59], v[60:61], v[50:51] op_sel_hi:[0,1,1]
.LBB0_1225:
	s_and_b64 vcc, exec, s[46:47]
	s_cbranch_vccnz .LBB0_1227
	s_waitcnt vmcnt(11)
	v_lshlrev_b32_e32 v58, 16, v112
	v_and_b32_e32 v59, 0xffff0000, v112
	v_lshlrev_b32_e32 v62, 16, v113
	v_and_b32_e32 v63, 0xffff0000, v113
	v_lshlrev_b32_e32 v82, 16, v114
	v_and_b32_e32 v83, 0xffff0000, v114
	v_lshlrev_b32_e32 v86, 16, v115
	v_and_b32_e32 v87, 0xffff0000, v115
	v_mul_f32_e32 v60, 0xbfb8aa3b, v58
	v_mul_f32_e32 v61, 0xbfb8aa3b, v59
	v_mul_f32_e32 v80, 0xbfb8aa3b, v62
	v_mul_f32_e32 v81, 0xbfb8aa3b, v63
	v_mul_f32_e32 v84, 0xbfb8aa3b, v82
	v_mul_f32_e32 v85, 0xbfb8aa3b, v83
	v_mul_f32_e32 v88, 0xbfb8aa3b, v86
	v_mul_f32_e32 v89, 0xbfb8aa3b, v87
	v_exp_f32_e32 v60, v60
	v_exp_f32_e32 v61, v61
	v_exp_f32_e32 v80, v80
	v_exp_f32_e32 v81, v81
	v_exp_f32_e32 v84, v84
	v_exp_f32_e32 v85, v85
	v_exp_f32_e32 v88, v88
	v_exp_f32_e32 v89, v89
	v_add_f32_e32 v60, 1.0, v60
	v_add_f32_e32 v61, 1.0, v61
	v_add_f32_e32 v80, 1.0, v80
	v_add_f32_e32 v81, 1.0, v81
	v_add_f32_e32 v84, 1.0, v84
	v_add_f32_e32 v85, 1.0, v85
	v_add_f32_e32 v88, 1.0, v88
	v_add_f32_e32 v89, 1.0, v89
	v_rcp_f32_e32 v60, v60
	v_rcp_f32_e32 v61, v61
	v_rcp_f32_e32 v80, v80
	v_rcp_f32_e32 v81, v81
	v_rcp_f32_e32 v84, v84
	v_rcp_f32_e32 v85, v85
	v_rcp_f32_e32 v88, v88
	v_rcp_f32_e32 v89, v89
	v_pk_mul_f32 v[58:59], v[60:61], v[58:59]
	v_pk_mul_f32 v[60:61], v[80:81], v[62:63]
	v_pk_mul_f32 v[62:63], v[84:85], v[82:83]
	v_pk_mul_f32 v[80:81], v[88:89], v[86:87]
	s_waitcnt lgkmcnt(1)
	v_pk_mul_f32 v[54:55], v[54:55], v[60:61]
	s_waitcnt lgkmcnt(0)
	v_pk_mul_f32 v[50:51], v[50:51], v[80:81]
	v_pk_mul_f32 v[48:49], v[48:49], v[62:63]
	v_pk_mul_f32 v[52:53], v[52:53], v[58:59]
.LBB0_1227:
	s_waitcnt lgkmcnt(1)
	v_cvt_pk_bf16_f32 v52, v52, v53
	v_cvt_pk_bf16_f32 v53, v54, v55
	s_waitcnt lgkmcnt(0)
	v_cvt_pk_bf16_f32 v54, v48, v49
	v_cvt_pk_bf16_f32 v55, v50, v51
	v_lshl_add_u64 v[48:49], s[84:85], 1, v[142:143]
	global_store_dwordx4 v[48:49], v[52:55], off sc1
	ds_read_b128 v[52:55], v57 offset:8448
	ds_read_b128 v[48:51], v57 offset:8464
	s_and_b64 vcc, exec, s[44:45]
	s_cbranch_vccnz .LBB0_1229
	ds_read_b32 v58, v56 offset:64
	s_waitcnt vmcnt(12)
	v_lshlrev_b32_e32 v60, 16, v76
	v_and_b32_e32 v61, 0xffff0000, v76
	s_waitcnt lgkmcnt(0)
	v_pk_fma_f32 v[52:53], v[58:59], v[60:61], v[52:53] op_sel_hi:[0,1,1]
	v_lshlrev_b32_e32 v60, 16, v77
	v_and_b32_e32 v61, 0xffff0000, v77
	v_pk_fma_f32 v[54:55], v[58:59], v[60:61], v[54:55] op_sel_hi:[0,1,1]
	v_lshlrev_b32_e32 v60, 16, v78
	v_and_b32_e32 v61, 0xffff0000, v78
	v_pk_fma_f32 v[48:49], v[58:59], v[60:61], v[48:49] op_sel_hi:[0,1,1]
	v_lshlrev_b32_e32 v60, 16, v79
	v_and_b32_e32 v61, 0xffff0000, v79
	v_pk_fma_f32 v[50:51], v[58:59], v[60:61], v[50:51] op_sel_hi:[0,1,1]
.LBB0_1229:
	s_and_b64 vcc, exec, s[46:47]
	s_cbranch_vccnz .LBB0_1231
	s_waitcnt vmcnt(12)
	v_lshlrev_b32_e32 v58, 16, v108
	v_and_b32_e32 v59, 0xffff0000, v108
	v_lshlrev_b32_e32 v62, 16, v109
	v_and_b32_e32 v63, 0xffff0000, v109
	v_lshlrev_b32_e32 v78, 16, v110
	v_and_b32_e32 v79, 0xffff0000, v110
	v_lshlrev_b32_e32 v82, 16, v111
	v_and_b32_e32 v83, 0xffff0000, v111
	v_mul_f32_e32 v60, 0xbfb8aa3b, v58
	v_mul_f32_e32 v61, 0xbfb8aa3b, v59
	v_mul_f32_e32 v76, 0xbfb8aa3b, v62
	v_mul_f32_e32 v77, 0xbfb8aa3b, v63
	v_mul_f32_e32 v80, 0xbfb8aa3b, v78
	v_mul_f32_e32 v81, 0xbfb8aa3b, v79
	v_mul_f32_e32 v84, 0xbfb8aa3b, v82
	v_mul_f32_e32 v85, 0xbfb8aa3b, v83
	v_exp_f32_e32 v60, v60
	v_exp_f32_e32 v61, v61
	v_exp_f32_e32 v76, v76
	v_exp_f32_e32 v77, v77
	v_exp_f32_e32 v80, v80
	v_exp_f32_e32 v81, v81
	v_exp_f32_e32 v84, v84
	v_exp_f32_e32 v85, v85
	v_add_f32_e32 v60, 1.0, v60
	v_add_f32_e32 v61, 1.0, v61
	v_add_f32_e32 v76, 1.0, v76
	v_add_f32_e32 v77, 1.0, v77
	v_add_f32_e32 v80, 1.0, v80
	v_add_f32_e32 v81, 1.0, v81
	v_add_f32_e32 v84, 1.0, v84
	v_add_f32_e32 v85, 1.0, v85
	v_rcp_f32_e32 v60, v60
	v_rcp_f32_e32 v61, v61
	v_rcp_f32_e32 v76, v76
	v_rcp_f32_e32 v77, v77
	v_rcp_f32_e32 v80, v80
	v_rcp_f32_e32 v81, v81
	v_rcp_f32_e32 v84, v84
	v_rcp_f32_e32 v85, v85
	v_pk_mul_f32 v[58:59], v[60:61], v[58:59]
	v_pk_mul_f32 v[60:61], v[76:77], v[62:63]
	v_pk_mul_f32 v[62:63], v[80:81], v[78:79]
	v_pk_mul_f32 v[76:77], v[84:85], v[82:83]
	s_waitcnt lgkmcnt(1)
	v_pk_mul_f32 v[54:55], v[54:55], v[60:61]
	s_waitcnt lgkmcnt(0)
	v_pk_mul_f32 v[50:51], v[50:51], v[76:77]
	v_pk_mul_f32 v[48:49], v[48:49], v[62:63]
	v_pk_mul_f32 v[52:53], v[52:53], v[58:59]
.LBB0_1231:
	s_waitcnt lgkmcnt(1)
	v_cvt_pk_bf16_f32 v52, v52, v53
	v_cvt_pk_bf16_f32 v53, v54, v55
	s_waitcnt lgkmcnt(0)
	v_cvt_pk_bf16_f32 v54, v48, v49
	v_cvt_pk_bf16_f32 v55, v50, v51
	v_lshl_add_u64 v[48:49], s[86:87], 1, v[142:143]
	global_store_dwordx4 v[48:49], v[52:55], off sc1
	ds_read_b128 v[52:55], v57 offset:10560
	ds_read_b128 v[48:51], v57 offset:10576
	s_and_b64 vcc, exec, s[44:45]
	s_cbranch_vccnz .LBB0_1233
	ds_read_b32 v58, v56 offset:80
	s_waitcnt vmcnt(13)
	v_lshlrev_b32_e32 v60, 16, v72
	v_and_b32_e32 v61, 0xffff0000, v72
	s_waitcnt lgkmcnt(0)
	v_pk_fma_f32 v[52:53], v[58:59], v[60:61], v[52:53] op_sel_hi:[0,1,1]
	v_lshlrev_b32_e32 v60, 16, v73
	v_and_b32_e32 v61, 0xffff0000, v73
	v_pk_fma_f32 v[54:55], v[58:59], v[60:61], v[54:55] op_sel_hi:[0,1,1]
	v_lshlrev_b32_e32 v60, 16, v74
	v_and_b32_e32 v61, 0xffff0000, v74
	v_pk_fma_f32 v[48:49], v[58:59], v[60:61], v[48:49] op_sel_hi:[0,1,1]
	v_lshlrev_b32_e32 v60, 16, v75
	v_and_b32_e32 v61, 0xffff0000, v75
	v_pk_fma_f32 v[50:51], v[58:59], v[60:61], v[50:51] op_sel_hi:[0,1,1]
.LBB0_1233:
	s_and_b64 vcc, exec, s[46:47]
	s_cbranch_vccnz .LBB0_1235
	s_waitcnt vmcnt(13)
	v_lshlrev_b32_e32 v58, 16, v104
	v_and_b32_e32 v59, 0xffff0000, v104
	v_lshlrev_b32_e32 v62, 16, v105
	v_and_b32_e32 v63, 0xffff0000, v105
	v_lshlrev_b32_e32 v74, 16, v106
	v_and_b32_e32 v75, 0xffff0000, v106
	v_lshlrev_b32_e32 v78, 16, v107
	v_and_b32_e32 v79, 0xffff0000, v107
	v_mul_f32_e32 v60, 0xbfb8aa3b, v58
	v_mul_f32_e32 v61, 0xbfb8aa3b, v59
	v_mul_f32_e32 v72, 0xbfb8aa3b, v62
	v_mul_f32_e32 v73, 0xbfb8aa3b, v63
	v_mul_f32_e32 v76, 0xbfb8aa3b, v74
	v_mul_f32_e32 v77, 0xbfb8aa3b, v75
	v_mul_f32_e32 v80, 0xbfb8aa3b, v78
	v_mul_f32_e32 v81, 0xbfb8aa3b, v79
	v_exp_f32_e32 v60, v60
	v_exp_f32_e32 v61, v61
	v_exp_f32_e32 v72, v72
	v_exp_f32_e32 v73, v73
	v_exp_f32_e32 v76, v76
	v_exp_f32_e32 v77, v77
	v_exp_f32_e32 v80, v80
	v_exp_f32_e32 v81, v81
	v_add_f32_e32 v60, 1.0, v60
	v_add_f32_e32 v61, 1.0, v61
	v_add_f32_e32 v72, 1.0, v72
	v_add_f32_e32 v73, 1.0, v73
	v_add_f32_e32 v76, 1.0, v76
	v_add_f32_e32 v77, 1.0, v77
	v_add_f32_e32 v80, 1.0, v80
	v_add_f32_e32 v81, 1.0, v81
	v_rcp_f32_e32 v60, v60
	v_rcp_f32_e32 v61, v61
	v_rcp_f32_e32 v72, v72
	v_rcp_f32_e32 v73, v73
	v_rcp_f32_e32 v76, v76
	v_rcp_f32_e32 v77, v77
	v_rcp_f32_e32 v80, v80
	v_rcp_f32_e32 v81, v81
	v_pk_mul_f32 v[58:59], v[60:61], v[58:59]
	v_pk_mul_f32 v[60:61], v[72:73], v[62:63]
	v_pk_mul_f32 v[62:63], v[76:77], v[74:75]
	v_pk_mul_f32 v[72:73], v[80:81], v[78:79]
	s_waitcnt lgkmcnt(1)
	v_pk_mul_f32 v[54:55], v[54:55], v[60:61]
	s_waitcnt lgkmcnt(0)
	v_pk_mul_f32 v[50:51], v[50:51], v[72:73]
	v_pk_mul_f32 v[48:49], v[48:49], v[62:63]
	v_pk_mul_f32 v[52:53], v[52:53], v[58:59]
.LBB0_1235:
	s_waitcnt lgkmcnt(1)
	v_cvt_pk_bf16_f32 v52, v52, v53
	v_cvt_pk_bf16_f32 v53, v54, v55
	s_waitcnt lgkmcnt(0)
	v_cvt_pk_bf16_f32 v54, v48, v49
	v_cvt_pk_bf16_f32 v55, v50, v51
	v_lshl_add_u64 v[48:49], s[88:89], 1, v[142:143]
	global_store_dwordx4 v[48:49], v[52:55], off sc1
	ds_read_b128 v[52:55], v57 offset:12672
	ds_read_b128 v[48:51], v57 offset:12688
	s_and_b64 vcc, exec, s[44:45]
	s_cbranch_vccnz .LBB0_1237
	ds_read_b32 v58, v56 offset:96
	s_waitcnt vmcnt(14)
	v_lshlrev_b32_e32 v60, 16, v68
	v_and_b32_e32 v61, 0xffff0000, v68
	s_waitcnt lgkmcnt(0)
	v_pk_fma_f32 v[52:53], v[58:59], v[60:61], v[52:53] op_sel_hi:[0,1,1]
	v_lshlrev_b32_e32 v60, 16, v69
	v_and_b32_e32 v61, 0xffff0000, v69
	v_pk_fma_f32 v[54:55], v[58:59], v[60:61], v[54:55] op_sel_hi:[0,1,1]
	v_lshlrev_b32_e32 v60, 16, v70
	v_and_b32_e32 v61, 0xffff0000, v70
	v_pk_fma_f32 v[48:49], v[58:59], v[60:61], v[48:49] op_sel_hi:[0,1,1]
	v_lshlrev_b32_e32 v60, 16, v71
	v_and_b32_e32 v61, 0xffff0000, v71
	v_pk_fma_f32 v[50:51], v[58:59], v[60:61], v[50:51] op_sel_hi:[0,1,1]
.LBB0_1237:
	s_and_b64 vcc, exec, s[46:47]
	s_cbranch_vccnz .LBB0_1239
	s_waitcnt vmcnt(14)
	v_lshlrev_b32_e32 v58, 16, v100
	v_and_b32_e32 v59, 0xffff0000, v100
	v_lshlrev_b32_e32 v62, 16, v101
	v_and_b32_e32 v63, 0xffff0000, v101
	v_lshlrev_b32_e32 v70, 16, v102
	v_and_b32_e32 v71, 0xffff0000, v102
	v_lshlrev_b32_e32 v74, 16, v103
	v_and_b32_e32 v75, 0xffff0000, v103
	v_mul_f32_e32 v60, 0xbfb8aa3b, v58
	v_mul_f32_e32 v61, 0xbfb8aa3b, v59
	v_mul_f32_e32 v68, 0xbfb8aa3b, v62
	v_mul_f32_e32 v69, 0xbfb8aa3b, v63
	v_mul_f32_e32 v72, 0xbfb8aa3b, v70
	v_mul_f32_e32 v73, 0xbfb8aa3b, v71
	v_mul_f32_e32 v76, 0xbfb8aa3b, v74
	v_mul_f32_e32 v77, 0xbfb8aa3b, v75
	v_exp_f32_e32 v60, v60
	v_exp_f32_e32 v61, v61
	v_exp_f32_e32 v68, v68
	v_exp_f32_e32 v69, v69
	v_exp_f32_e32 v72, v72
	v_exp_f32_e32 v73, v73
	v_exp_f32_e32 v76, v76
	v_exp_f32_e32 v77, v77
	v_add_f32_e32 v60, 1.0, v60
	v_add_f32_e32 v61, 1.0, v61
	v_add_f32_e32 v68, 1.0, v68
	v_add_f32_e32 v69, 1.0, v69
	v_add_f32_e32 v72, 1.0, v72
	v_add_f32_e32 v73, 1.0, v73
	v_add_f32_e32 v76, 1.0, v76
	v_add_f32_e32 v77, 1.0, v77
	v_rcp_f32_e32 v60, v60
	v_rcp_f32_e32 v61, v61
	v_rcp_f32_e32 v68, v68
	v_rcp_f32_e32 v69, v69
	v_rcp_f32_e32 v72, v72
	v_rcp_f32_e32 v73, v73
	v_rcp_f32_e32 v76, v76
	v_rcp_f32_e32 v77, v77
	v_pk_mul_f32 v[58:59], v[60:61], v[58:59]
	v_pk_mul_f32 v[60:61], v[68:69], v[62:63]
	v_pk_mul_f32 v[62:63], v[72:73], v[70:71]
	v_pk_mul_f32 v[68:69], v[76:77], v[74:75]
	s_waitcnt lgkmcnt(1)
	v_pk_mul_f32 v[54:55], v[54:55], v[60:61]
	s_waitcnt lgkmcnt(0)
	v_pk_mul_f32 v[50:51], v[50:51], v[68:69]
	v_pk_mul_f32 v[48:49], v[48:49], v[62:63]
	v_pk_mul_f32 v[52:53], v[52:53], v[58:59]
.LBB0_1239:
	s_waitcnt lgkmcnt(1)
	v_cvt_pk_bf16_f32 v52, v52, v53
	v_cvt_pk_bf16_f32 v53, v54, v55
	s_waitcnt lgkmcnt(0)
	v_cvt_pk_bf16_f32 v54, v48, v49
	v_cvt_pk_bf16_f32 v55, v50, v51
	v_lshl_add_u64 v[48:49], s[90:91], 1, v[142:143]
	global_store_dwordx4 v[48:49], v[52:55], off sc1
	ds_read_b128 v[52:55], v57 offset:14784
	ds_read_b128 v[48:51], v57 offset:14800
	s_and_b64 vcc, exec, s[44:45]
	s_cbranch_vccnz .LBB0_1241
	ds_read_b32 v56, v56 offset:112
	s_waitcnt vmcnt(15)
	v_lshlrev_b32_e32 v58, 16, v64
	v_and_b32_e32 v59, 0xffff0000, v64
	s_waitcnt lgkmcnt(0)
	v_pk_fma_f32 v[52:53], v[56:57], v[58:59], v[52:53] op_sel_hi:[0,1,1]
	v_lshlrev_b32_e32 v58, 16, v65
	v_and_b32_e32 v59, 0xffff0000, v65
	v_pk_fma_f32 v[54:55], v[56:57], v[58:59], v[54:55] op_sel_hi:[0,1,1]
	v_lshlrev_b32_e32 v58, 16, v66
	v_and_b32_e32 v59, 0xffff0000, v66
	v_pk_fma_f32 v[48:49], v[56:57], v[58:59], v[48:49] op_sel_hi:[0,1,1]
	v_lshlrev_b32_e32 v58, 16, v67
	v_and_b32_e32 v59, 0xffff0000, v67
	v_pk_fma_f32 v[50:51], v[56:57], v[58:59], v[50:51] op_sel_hi:[0,1,1]
.LBB0_1241:
	s_and_b64 vcc, exec, s[46:47]
	s_cbranch_vccnz .LBB0_1243
	s_waitcnt vmcnt(15)
	v_lshlrev_b32_e32 v56, 16, v92
	v_and_b32_e32 v57, 0xffff0000, v92
	v_lshlrev_b32_e32 v60, 16, v93
	v_and_b32_e32 v61, 0xffff0000, v93
	v_lshlrev_b32_e32 v64, 16, v94
	v_and_b32_e32 v65, 0xffff0000, v94
	v_lshlrev_b32_e32 v68, 16, v95
	v_and_b32_e32 v69, 0xffff0000, v95
	v_mul_f32_e32 v58, 0xbfb8aa3b, v56
	v_mul_f32_e32 v59, 0xbfb8aa3b, v57
	v_mul_f32_e32 v62, 0xbfb8aa3b, v60
	v_mul_f32_e32 v63, 0xbfb8aa3b, v61
	v_mul_f32_e32 v66, 0xbfb8aa3b, v64
	v_mul_f32_e32 v67, 0xbfb8aa3b, v65
	v_mul_f32_e32 v70, 0xbfb8aa3b, v68
	v_mul_f32_e32 v71, 0xbfb8aa3b, v69
	v_exp_f32_e32 v58, v58
	v_exp_f32_e32 v59, v59
	v_exp_f32_e32 v62, v62
	v_exp_f32_e32 v63, v63
	v_exp_f32_e32 v66, v66
	v_exp_f32_e32 v67, v67
	v_exp_f32_e32 v70, v70
	v_exp_f32_e32 v71, v71
	v_add_f32_e32 v58, 1.0, v58
	v_add_f32_e32 v59, 1.0, v59
	v_add_f32_e32 v62, 1.0, v62
	v_add_f32_e32 v63, 1.0, v63
	v_add_f32_e32 v66, 1.0, v66
	v_add_f32_e32 v67, 1.0, v67
	v_add_f32_e32 v70, 1.0, v70
	v_add_f32_e32 v71, 1.0, v71
	v_rcp_f32_e32 v58, v58
	v_rcp_f32_e32 v59, v59
	v_rcp_f32_e32 v62, v62
	v_rcp_f32_e32 v63, v63
	v_rcp_f32_e32 v66, v66
	v_rcp_f32_e32 v67, v67
	v_rcp_f32_e32 v70, v70
	v_rcp_f32_e32 v71, v71
	v_pk_mul_f32 v[56:57], v[58:59], v[56:57]
	v_pk_mul_f32 v[58:59], v[62:63], v[60:61]
	v_pk_mul_f32 v[60:61], v[66:67], v[64:65]
	v_pk_mul_f32 v[62:63], v[70:71], v[68:69]
	s_waitcnt lgkmcnt(1)
	v_pk_mul_f32 v[54:55], v[54:55], v[58:59]
	s_waitcnt lgkmcnt(0)
	v_pk_mul_f32 v[50:51], v[50:51], v[62:63]
	v_pk_mul_f32 v[48:49], v[48:49], v[60:61]
	v_pk_mul_f32 v[52:53], v[52:53], v[56:57]
